# post1 token loop: all 18 loads of an iteration issued in two groups (fresh destination registers) instead of six serial load/wait steps
# speedup vs baseline: 1.0090x; 1.0090x over previous
; __device__ __forceinline__ float bf2f(bf16_t h) { return __uint_as_float(((unsigned)h) << 16); }
; __device__ __forceinline__ bf16_t f2bf(float f) { return (bf16_t)(cvt_pk(f, 0.f) & 0xffffu); }
; __device__ __forceinline__ void phase_post1(const Ctx& a, int l, LAS unsigned char* lds) {
;     ...
;         const float2 cs = t64[tk * 32 + i];
;         bf16_t xa[8], xb2[8];
; #pragma unroll
;         for (int jj = 0; jj < 8; ++jj) { const bf16_t* p = pr + C_MQ + ((lane >> 5) + 2 * jj) * 64; xa[jj] = p[i]; xb2[jj] = p[i + 32]; }
; #pragma unroll
;         for (int jj = 0; jj < 8; ++jj) {
;             int vec = (lane >> 5) + 2 * jj;
;             bf16_t* p = pr + C_MQ + vec * 64;
;             float x1 = bf2f(xa[jj]), x2 = bf2f(xb2[jj]);
;             float ss = x1 * x1 + x2 * x2;
; #pragma unroll
;             for (int o = 16; o > 0; o >>= 1) ss += __shfl_xor(ss, o);
;             float r = rsqrtf(ss * (1.f / 64.f) + EPS);
;             const float* g = (vec < 8) ? gq : gk;
;             float y1 = x1 * r * g[i], y2 = x2 * r * g[i + 32];
;             float o1 = y1 * cs.x - y2 * cs.y, o2 = y2 * cs.x + y1 * cs.y;
;             if (vec < 8) { o1 *= 0.125f * LOG2E; o2 *= 0.125f * LOG2E; }
;             p[i] = f2bf(o1); p[i + 32] = f2bf(o2);
.LBB0_520:
	s_or_b64 exec, exec, s[40:41]
	v_readlane_b32 s0, v253, 63
	v_ashrrev_i32_e32 v9, 31, v8
	v_readlane_b32 s1, v254, 0
	v_mov_b32_e32 v13, v145
	v_mov_b32_e32 v15, v145
	v_lshl_add_u64 v[30:31], v[8:9], 3, s[0:1]
	s_mov_b64 s[0:1], 0x1350
	v_lshl_add_u64 v[36:37], v[32:33], 0, s[0:1]
	v_lshl_add_u64 v[32:33], v[36:37], 0, v[12:13]
	v_lshl_add_u64 v[38:39], v[32:33], 0, v[14:15]
	global_load_dwordx2 v[30:31], v[30:31], off
	s_nop 0
	global_load_ushort v7, v[38:39], off
	global_load_ushort v9, v[38:39], off offset:64
	global_load_ushort v85, v[38:39], off offset:256
	global_load_ushort v86, v[38:39], off offset:320
	global_load_ushort v87, v[38:39], off offset:512
	global_load_ushort v88, v[38:39], off offset:576
	global_load_ushort v89, v[38:39], off offset:768
	global_load_ushort v90, v[38:39], off offset:832
	global_load_ushort v91, v[38:39], off offset:1024
	global_load_ushort v92, v[38:39], off offset:1088
	global_load_ushort v93, v[38:39], off offset:1280
	global_load_ushort v94, v[38:39], off offset:1344
	global_load_ushort v95, v[38:39], off offset:1536
	global_load_ushort v96, v[38:39], off offset:1600
	global_load_ushort v97, v[38:39], off offset:1792
	global_load_ushort v98, v[38:39], off offset:1856
	flat_load_dword v99, v[4:5]
	flat_load_dword v100, v[4:5] offset:128
	flat_load_dword v25, v[2:3]
	flat_load_dword v23, v[2:3] offset:128
	s_mov_b32 s0, 0x358637bd
	s_mov_b32 s8, 0x3c800000
	v_lshl_add_u64 v[40:41], v[36:37], 0, v[14:15]
	v_lshl_add_u64 v[40:41], v[40:41], 0, v[12:13]
	v_mov_b32_e32 v17, v145
	v_lshl_add_u64 v[42:43], v[36:37], 0, v[16:17]
	v_add_u32_e32 v6, s9, v6
	v_add_u32_e32 v8, s26, v8
	s_waitcnt vmcnt(0)
	v_lshlrev_b32_e32 v54, 16, v7
	v_lshlrev_b32_e32 v55, 16, v9
	s_waitcnt lgkmcnt(0)
	v_pk_mul_f32 v[34:35], v[54:55], v[54:55]
	s_waitcnt vmcnt(1)
	v_lshlrev_b32_e32 v44, 16, v85
	s_waitcnt vmcnt(0)
	v_lshlrev_b32_e32 v45, 16, v86
	v_pk_mul_f32 v[46:47], v[44:45], v[44:45]
	v_mov_b32_e32 v57, v34
	v_mov_b32_e32 v56, v46
	v_mov_b32_e32 v34, v47
	v_pk_add_f32 v[34:35], v[56:57], v[34:35]
	ds_bpermute_b32 v47, v48, v35
	ds_bpermute_b32 v46, v48, v34
	s_waitcnt lgkmcnt(0)
	v_pk_add_f32 v[34:35], v[34:35], v[46:47]
	ds_bpermute_b32 v47, v49, v35
	ds_bpermute_b32 v46, v49, v34
	s_waitcnt lgkmcnt(0)
	v_pk_add_f32 v[34:35], v[34:35], v[46:47]
	ds_bpermute_b32 v47, v50, v35
	ds_bpermute_b32 v46, v50, v34
	s_waitcnt lgkmcnt(0)
	v_pk_add_f32 v[34:35], v[34:35], v[46:47]
	ds_bpermute_b32 v47, v51, v35
	ds_bpermute_b32 v46, v51, v34
	s_waitcnt lgkmcnt(0)
	v_pk_add_f32 v[34:35], v[34:35], v[46:47]
	ds_bpermute_b32 v47, v52, v35
	ds_bpermute_b32 v46, v52, v34
	s_waitcnt lgkmcnt(0)
	v_pk_add_f32 v[46:47], v[34:35], v[46:47]
	v_mov_b64_e32 v[34:35], s[0:1]
	v_pk_fma_f32 v[46:47], v[46:47], s[8:9], v[34:35] op_sel_hi:[1,0,0]
	s_nop 0
	v_mul_f32_e32 v7, 0x4b800000, v47
	v_cmp_gt_f32_e64 s[36:37], s88, v47
	v_cmp_gt_f32_e64 s[0:1], s88, v46
	s_nop 0
	v_cndmask_b32_e64 v7, v47, v7, s[36:37]
	v_rsq_f32_e32 v7, v7
	s_nop 0
	v_mul_f32_e32 v9, 0x45800000, v7
	v_cndmask_b32_e64 v7, v7, v9, s[36:37]
	v_mul_f32_e32 v9, v7, v54
	v_mul_f32_e32 v7, v7, v55
	v_mul_f32_e32 v7, v23, v7
	v_mul_f32_e32 v9, v25, v9
	v_mul_f32_e32 v11, v31, v7
	v_fma_f32 v11, v30, v9, -v11
	v_mul_f32_e32 v7, v30, v7
	v_fmac_f32_e32 v7, v31, v9
	v_mul_f32_e32 v9, 0x3e38aa3b, v11
	v_mul_f32_e32 v19, 0x3e38aa3b, v7
	v_cvt_pk_bf16_f32 v21, v9, s0
	v_cvt_pk_bf16_f32 v19, v19, s0
	global_store_short v[40:41], v19, off offset:64
	v_mul_f32_e32 v19, 0x4b800000, v46
	v_cndmask_b32_e64 v19, v46, v19, s[0:1]
	v_rsq_f32_e32 v19, v19
	global_store_short v[40:41], v21, off
	v_mul_f32_e32 v21, 0x45800000, v19
	v_cndmask_b32_e64 v19, v19, v21, s[0:1]
	v_mul_f32_e32 v21, v19, v44
	v_mul_f32_e32 v19, v19, v45
	v_mul_f32_e32 v19, v23, v19
	v_mul_f32_e32 v21, v25, v21
	v_mul_f32_e32 v38, v31, v19
	v_fma_f32 v38, v30, v21, -v38
	v_mul_f32_e32 v19, v30, v19
	v_fmac_f32_e32 v19, v31, v21
	v_mul_f32_e32 v21, 0x3e38aa3b, v38
	v_cvt_pk_bf16_f32 v21, v21, s0
	v_lshl_add_u64 v[38:39], v[32:33], 0, v[16:17]
	global_store_short v[38:39], v21, off
	v_lshl_add_u64 v[38:39], v[42:43], 0, v[12:13]
	v_mul_f32_e32 v19, 0x3e38aa3b, v19
	v_cvt_pk_bf16_f32 v17, v19, s0
	global_store_short v[38:39], v17, off offset:64
	v_mov_b32_e32 v19, v145
	v_lshl_add_u64 v[38:39], v[36:37], 0, v[18:19]
	v_lshl_add_u64 v[40:41], v[32:33], 0, v[18:19]
	v_lshl_add_u64 v[38:39], v[38:39], 0, v[12:13]
	v_mov_b32_e32 v21, v145
	v_lshl_add_u64 v[44:45], v[36:37], 0, v[20:21]
	s_waitcnt vmcnt(15)
	v_lshlrev_b32_e32 v42, 16, v87
	s_waitcnt vmcnt(14)
	v_lshlrev_b32_e32 v43, 16, v88
	s_waitcnt vmcnt(13)
	v_lshlrev_b32_e32 v46, 16, v89
	s_waitcnt vmcnt(12)
	v_lshlrev_b32_e32 v47, 16, v90
	v_pk_mul_f32 v[56:57], v[42:43], v[42:43]
	v_pk_mul_f32 v[58:59], v[46:47], v[46:47]
	v_mov_b32_e32 v61, v56
	v_mov_b32_e32 v60, v58
	v_mov_b32_e32 v56, v59
	v_pk_add_f32 v[56:57], v[60:61], v[56:57]
	ds_bpermute_b32 v59, v48, v57
	ds_bpermute_b32 v58, v48, v56
	s_waitcnt lgkmcnt(0)
	v_pk_add_f32 v[56:57], v[56:57], v[58:59]
	ds_bpermute_b32 v59, v49, v57
	ds_bpermute_b32 v58, v49, v56
	s_waitcnt lgkmcnt(0)
	v_pk_add_f32 v[56:57], v[56:57], v[58:59]
	ds_bpermute_b32 v59, v50, v57
	ds_bpermute_b32 v58, v50, v56
	s_waitcnt lgkmcnt(0)
	v_pk_add_f32 v[56:57], v[56:57], v[58:59]
	ds_bpermute_b32 v59, v51, v57
	ds_bpermute_b32 v58, v51, v56
	s_waitcnt lgkmcnt(0)
	v_pk_add_f32 v[56:57], v[56:57], v[58:59]
	ds_bpermute_b32 v59, v52, v57
	ds_bpermute_b32 v58, v52, v56
	s_waitcnt lgkmcnt(0)
; __device__ __forceinline__ float bf2f(bf16_t h) { return __uint_as_float(((unsigned)h) << 16); }
; __device__ __forceinline__ bf16_t f2bf(float f) { return (bf16_t)(cvt_pk(f, 0.f) & 0xffffu); }
; __device__ __forceinline__ void phase_post1(const Ctx& a, int l, LAS unsigned char* lds) {
;     ...
;         for (int jj = 0; jj < 8; ++jj) {
;             int vec = (lane >> 5) + 2 * jj;
;             bf16_t* p = pr + C_MQ + vec * 64;
;             float x1 = bf2f(xa[jj]), x2 = bf2f(xb2[jj]);
;             float ss = x1 * x1 + x2 * x2;
; #pragma unroll
;             for (int o = 16; o > 0; o >>= 1) ss += __shfl_xor(ss, o);
;             float r = rsqrtf(ss * (1.f / 64.f) + EPS);
;             const float* g = (vec < 8) ? gq : gk;
;             float y1 = x1 * r * g[i], y2 = x2 * r * g[i + 32];
;             float o1 = y1 * cs.x - y2 * cs.y, o2 = y2 * cs.x + y1 * cs.y;
;             if (vec < 8) { o1 *= 0.125f * LOG2E; o2 *= 0.125f * LOG2E; }
;             p[i] = f2bf(o1); p[i + 32] = f2bf(o2);
;         }
;     }
	v_pk_add_f32 v[56:57], v[56:57], v[58:59]
	s_nop 0
	v_pk_fma_f32 v[56:57], v[56:57], s[8:9], v[34:35] op_sel_hi:[1,0,0]
	s_nop 0
	v_mul_f32_e32 v17, 0x4b800000, v57
	v_cmp_gt_f32_e64 s[36:37], s88, v57
	v_cmp_gt_f32_e64 s[0:1], s88, v56
	s_nop 0
	v_cndmask_b32_e64 v17, v57, v17, s[36:37]
	v_rsq_f32_e32 v17, v17
	s_nop 0
	v_mul_f32_e32 v19, 0x45800000, v17
	v_cndmask_b32_e64 v17, v17, v19, s[36:37]
	v_mul_f32_e32 v19, v17, v42
	v_mul_f32_e32 v17, v17, v43
	v_mul_f32_e32 v17, v23, v17
	v_mul_f32_e32 v19, v25, v19
	v_mul_f32_e32 v42, v31, v17
	v_mul_f32_e32 v17, v30, v17
	v_fmac_f32_e32 v17, v31, v19
	v_mul_f32_e32 v17, 0x3e38aa3b, v17
	v_cvt_pk_bf16_f32 v17, v17, s0
	global_store_short v[38:39], v17, off offset:64
	v_mul_f32_e32 v17, 0x4b800000, v56
	v_cndmask_b32_e64 v17, v56, v17, s[0:1]
	v_rsq_f32_e32 v17, v17
	v_fma_f32 v42, v30, v19, -v42
	v_mul_f32_e32 v19, 0x3e38aa3b, v42
	v_cvt_pk_bf16_f32 v19, v19, s0
	global_store_short v[40:41], v19, off
	v_mul_f32_e32 v19, 0x45800000, v17
	v_cndmask_b32_e64 v17, v17, v19, s[0:1]
	v_mul_f32_e32 v19, v17, v46
	v_mul_f32_e32 v17, v17, v47
	v_mul_f32_e32 v17, v23, v17
	v_mul_f32_e32 v19, v25, v19
	v_mul_f32_e32 v23, v31, v17
	v_fma_f32 v23, v30, v19, -v23
	v_mul_f32_e32 v17, v30, v17
	v_fmac_f32_e32 v17, v31, v19
	v_mul_f32_e32 v19, 0x3e38aa3b, v23
	v_mul_f32_e32 v17, 0x3e38aa3b, v17
	v_cvt_pk_bf16_f32 v19, v19, s0
	v_lshl_add_u64 v[38:39], v[32:33], 0, v[20:21]
	global_store_short v[38:39], v19, off
	v_cvt_pk_bf16_f32 v17, v17, s0
	v_lshl_add_u64 v[38:39], v[44:45], 0, v[12:13]
	global_store_short v[38:39], v17, off offset:64
	s_nop 0
	s_waitcnt vmcnt(0)
	v_lshlrev_b32_e32 v39, 16, v92
	v_lshlrev_b32_e32 v38, 16, v91
	v_lshlrev_b32_e32 v47, 16, v94
	v_lshlrev_b32_e32 v46, 16, v93
	v_pk_mul_f32 v[40:41], v[38:39], v[38:39]
	v_pk_mul_f32 v[54:55], v[46:47], v[46:47]
	v_mov_b32_e32 v59, v40
	v_mov_b32_e32 v58, v54
	v_mov_b32_e32 v40, v55
	v_pk_add_f32 v[40:41], v[58:59], v[40:41]
	ds_bpermute_b32 v55, v48, v41
	ds_bpermute_b32 v54, v48, v40
	v_mov_b32_e32 v23, v145
	v_lshl_add_u64 v[42:43], v[36:37], 0, v[22:23]
	v_lshl_add_u64 v[44:45], v[32:33], 0, v[22:23]
	v_lshl_add_u64 v[42:43], v[42:43], 0, v[12:13]
	s_waitcnt lgkmcnt(0)
	v_pk_add_f32 v[40:41], v[40:41], v[54:55]
	ds_bpermute_b32 v55, v49, v41
	ds_bpermute_b32 v54, v49, v40
	v_mov_b32_e32 v25, v145
	v_lshl_add_u64 v[56:57], v[36:37], 0, v[24:25]
	v_mov_b32_e32 v29, v145
	s_waitcnt lgkmcnt(0)
	v_pk_add_f32 v[40:41], v[40:41], v[54:55]
	ds_bpermute_b32 v55, v50, v41
	ds_bpermute_b32 v54, v50, v40
	s_waitcnt lgkmcnt(0)
	v_pk_add_f32 v[40:41], v[40:41], v[54:55]
	ds_bpermute_b32 v55, v51, v41
	ds_bpermute_b32 v54, v51, v40
	s_waitcnt lgkmcnt(0)
	v_pk_add_f32 v[40:41], v[40:41], v[54:55]
	ds_bpermute_b32 v55, v52, v41
	ds_bpermute_b32 v54, v52, v40
	s_waitcnt lgkmcnt(0)
	v_pk_add_f32 v[40:41], v[40:41], v[54:55]
	s_nop 0
	v_pk_fma_f32 v[40:41], v[40:41], s[8:9], v[34:35] op_sel_hi:[1,0,0]
	s_nop 0
	v_mul_f32_e32 v21, 0x4b800000, v41
	v_cmp_gt_f32_e64 s[36:37], s88, v41
	v_cmp_gt_f32_e64 s[0:1], s88, v40
	s_nop 0
	v_cndmask_b32_e64 v21, v41, v21, s[36:37]
	v_rsq_f32_e32 v21, v21
	s_nop 0
	v_mul_f32_e32 v23, 0x45800000, v21
	v_cndmask_b32_e64 v21, v21, v23, s[36:37]
	v_mul_f32_e32 v23, v21, v38
	v_mul_f32_e32 v21, v21, v39
	v_lshl_add_u64 v[38:39], v[32:33], 0, v[24:25]
	v_mul_f32_e32 v23, v99, v23
	v_mul_f32_e32 v21, v100, v21
	v_mul_f32_e32 v27, v31, v21
	v_mul_f32_e32 v21, v30, v21
	v_fmac_f32_e32 v21, v31, v23
	v_cvt_pk_bf16_f32 v21, v21, s0
	global_store_short v[42:43], v21, off offset:64
	v_mul_f32_e32 v21, 0x4b800000, v40
	v_cndmask_b32_e64 v21, v40, v21, s[0:1]
	v_rsq_f32_e32 v21, v21
	v_fma_f32 v27, v30, v23, -v27
	v_cvt_pk_bf16_f32 v23, v27, s0
	global_store_short v[44:45], v23, off
	v_mul_f32_e32 v23, 0x45800000, v21
	v_cndmask_b32_e64 v21, v21, v23, s[0:1]
	v_mul_f32_e32 v23, v21, v46
	v_mul_f32_e32 v21, v21, v47
	v_mul_f32_e32 v21, v100, v21
	v_mul_f32_e32 v23, v99, v23
	v_mul_f32_e32 v27, v31, v21
	v_fma_f32 v27, v30, v23, -v27
	v_mul_f32_e32 v21, v30, v21
	v_fmac_f32_e32 v21, v31, v23
	v_cvt_pk_bf16_f32 v23, v27, s0
	global_store_short v[38:39], v23, off
	v_cvt_pk_bf16_f32 v21, v21, s0
	v_lshl_add_u64 v[38:39], v[56:57], 0, v[12:13]
	global_store_short v[38:39], v21, off offset:64
	v_lshlrev_b32_e32 v39, 16, v96
	v_lshlrev_b32_e32 v38, 16, v95
	v_lshlrev_b32_e32 v47, 16, v98
	v_lshlrev_b32_e32 v46, 16, v97
	v_pk_mul_f32 v[40:41], v[38:39], v[38:39]
	v_pk_mul_f32 v[54:55], v[46:47], v[46:47]
	v_mov_b32_e32 v57, v40
	v_mov_b32_e32 v56, v54
	v_mov_b32_e32 v40, v55
	v_pk_add_f32 v[40:41], v[56:57], v[40:41]
	ds_bpermute_b32 v55, v48, v41
	ds_bpermute_b32 v54, v48, v40
	v_mov_b32_e32 v27, v145
	v_lshl_add_u64 v[42:43], v[36:37], 0, v[26:27]
	v_lshl_add_u64 v[42:43], v[42:43], 0, v[12:13]
	v_lshl_add_u64 v[44:45], v[32:33], 0, v[26:27]
	s_waitcnt lgkmcnt(0)
	v_pk_add_f32 v[40:41], v[40:41], v[54:55]
	ds_bpermute_b32 v55, v49, v41
	ds_bpermute_b32 v54, v49, v40
	v_lshl_add_u64 v[36:37], v[36:37], 0, v[28:29]
	s_waitcnt lgkmcnt(0)
	v_pk_add_f32 v[40:41], v[40:41], v[54:55]
	ds_bpermute_b32 v55, v50, v41
	ds_bpermute_b32 v54, v50, v40
	s_waitcnt lgkmcnt(0)
	v_pk_add_f32 v[40:41], v[40:41], v[54:55]
	ds_bpermute_b32 v55, v51, v41
	ds_bpermute_b32 v54, v51, v40
	s_waitcnt lgkmcnt(0)
	v_pk_add_f32 v[40:41], v[40:41], v[54:55]
	ds_bpermute_b32 v55, v52, v41
	ds_bpermute_b32 v54, v52, v40
	s_waitcnt lgkmcnt(0)
	v_pk_add_f32 v[40:41], v[40:41], v[54:55]
	s_nop 0
	v_pk_fma_f32 v[34:35], v[40:41], s[8:9], v[34:35] op_sel_hi:[1,0,0]
	s_nop 0
	v_mul_f32_e32 v7, 0x4b800000, v35
	v_cmp_gt_f32_e64 s[36:37], s88, v35
	v_cmp_gt_f32_e64 s[0:1], s88, v34
	s_nop 0
	v_cndmask_b32_e64 v7, v35, v7, s[36:37]
	v_rsq_f32_e32 v7, v7
	s_nop 0
	v_mul_f32_e32 v9, 0x45800000, v7
	v_cndmask_b32_e64 v7, v7, v9, s[36:37]
	v_mul_f32_e32 v9, v7, v38
	v_mul_f32_e32 v7, v7, v39
	v_mul_f32_e32 v7, v100, v7
	v_mul_f32_e32 v9, v99, v9
	v_mul_f32_e32 v11, v31, v7
	v_mul_f32_e32 v7, v30, v7
	v_fmac_f32_e32 v7, v31, v9
	v_cvt_pk_bf16_f32 v7, v7, s0
	global_store_short v[42:43], v7, off offset:64
	v_mul_f32_e32 v7, 0x4b800000, v34
	v_cndmask_b32_e64 v7, v34, v7, s[0:1]
	v_rsq_f32_e32 v7, v7
	v_fma_f32 v11, v30, v9, -v11
	v_cvt_pk_bf16_f32 v9, v11, s0
	global_store_short v[44:45], v9, off
	v_mul_f32_e32 v9, 0x45800000, v7
	v_cndmask_b32_e64 v7, v7, v9, s[0:1]
	v_mul_f32_e32 v9, v7, v46
	v_mul_f32_e32 v7, v7, v47
	v_mul_f32_e32 v7, v100, v7
	v_mul_f32_e32 v9, v99, v9
	v_mul_f32_e32 v11, v31, v7
	v_mul_f32_e32 v7, v30, v7
	v_fma_f32 v11, v30, v9, -v11
	v_fmac_f32_e32 v7, v31, v9
	v_cvt_pk_bf16_f32 v9, v11, s0
	v_cvt_pk_bf16_f32 v7, v7, s0
	s_movk_i32 s0, 0x1fff
	v_lshl_add_u64 v[30:31], v[32:33], 0, v[28:29]
	v_cmp_lt_i32_e64 s[0:1], s0, v6
	global_store_short v[30:31], v9, off
	v_lshl_add_u64 v[30:31], v[36:37], 0, v[12:13]
	s_or_b64 s[38:39], s[0:1], s[38:39]
	global_store_short v[30:31], v7, off offset:64
	s_andn2_b64 exec, exec, s[38:39]
	s_cbranch_execz .LBB0_523
; __device__ __forceinline__ float lo_bf(unsigned u) { return __uint_as_float(u << 16); }
; __device__ __forceinline__ float hi_bf(unsigned u) { return __uint_as_float(u & 0xffff0000u); }
; __device__ __forceinline__ int fresh_bid() { int t; asm volatile("s_mov_b32 %0, %1" : "=s"(t) : "s"(blockIdx.x)); return t; }
; __device__ __forceinline__ void phase_post1(const Ctx& a, int l, LAS unsigned char* lds) {
;     ...
;     for (int tk = fresh_bid() * 8 + wv; tk < SEQ; tk += gridDim.x * 8) {
;         bf16_t* pr = pa + (size_t)tk * PA;
;         u32x2 cq = *(const u32x2*)(pr + C_CQ + lane * 4);
;         float s1 = lo_bf(cq[0]) * lo_bf(cq[0]) + hi_bf(cq[0]) * hi_bf(cq[0]) + lo_bf(cq[1]) * lo_bf(cq[1]) + hi_bf(cq[1]) * hi_bf(cq[1]);
;         unsigned ck = *(const unsigned*)(pr + C_CKV + lane * 2);
;         float s2 = lo_bf(ck) * lo_bf(ck) + hi_bf(ck) * hi_bf(ck);
;         s1 = wave_sum(s1); s2 = wave_sum(s2);
;         if (lane == 0) { rq[tk] = rsqrtf(s1 * (1.f / 256.f) + EPS); rkv[tk] = rsqrtf(s2 * (1.f / 128.f) + EPS); }
.LBB0_521:
	v_ashrrev_i32_e32 v7, 31, v6
	v_lshlrev_b64 v[30:31], 13, v[6:7]
	v_lshl_add_u64 v[32:33], s[70:71], 0, v[30:31]
	v_lshl_add_u64 v[30:31], v[32:33], 0, v[144:145]
	global_load_dwordx2 v[30:31], v[30:31], off
	v_mov_b32_e32 v11, v145
	v_lshl_add_u64 v[36:37], v[32:33], 0, v[10:11]
	global_load_dword v84, v[36:37], off offset:512
	s_waitcnt vmcnt(0)
	v_lshlrev_b32_e32 v35, 16, v31
	v_lshlrev_b32_e32 v34, 16, v30
	v_and_b32_e32 v9, 0xffff0000, v30
	v_pk_mul_f32 v[34:35], v[34:35], v[34:35]
	v_and_b32_e32 v31, 0xffff0000, v31
	v_fma_f32 v9, v9, v9, v34
	v_add_f32_e32 v35, v35, v9
	s_waitcnt vmcnt(0)
	v_lshlrev_b32_e32 v30, 16, v84
	v_and_b32_e32 v9, 0xffff0000, v84
	v_mul_f32_e32 v34, v9, v9
	v_pk_fma_f32 v[30:31], v[30:31], v[30:31], v[34:35]
	ds_bpermute_b32 v35, v1, v31
	ds_bpermute_b32 v34, v1, v30
	s_waitcnt lgkmcnt(0)
	v_pk_add_f32 v[30:31], v[30:31], v[34:35]
	ds_bpermute_b32 v35, v48, v31
	ds_bpermute_b32 v34, v48, v30
	s_waitcnt lgkmcnt(0)
	v_pk_add_f32 v[30:31], v[30:31], v[34:35]
	ds_bpermute_b32 v35, v49, v31
	ds_bpermute_b32 v34, v49, v30
	s_waitcnt lgkmcnt(0)
	v_pk_add_f32 v[30:31], v[30:31], v[34:35]
	ds_bpermute_b32 v35, v50, v31
	ds_bpermute_b32 v34, v50, v30
	s_waitcnt lgkmcnt(0)
	v_pk_add_f32 v[30:31], v[30:31], v[34:35]
	ds_bpermute_b32 v35, v51, v31
	ds_bpermute_b32 v34, v51, v30
	s_waitcnt lgkmcnt(0)
	v_pk_add_f32 v[30:31], v[30:31], v[34:35]
	ds_bpermute_b32 v35, v52, v31
	ds_bpermute_b32 v34, v52, v30
	s_and_saveexec_b64 s[40:41], vcc
	s_cbranch_execz .LBB0_520
	v_readlane_b32 s0, v254, 50
	v_lshlrev_b64 v[36:37], 2, v[6:7]
	v_readlane_b32 s1, v254, 51
	s_waitcnt lgkmcnt(0)
	v_pk_add_f32 v[30:31], v[30:31], v[34:35]
	v_lshl_add_u64 v[38:39], s[0:1], 0, v[36:37]
	s_brev_b32 s0, 60
	s_mov_b32 s1, 0x3b800000
	v_pk_fma_f32 v[30:31], v[30:31], s[0:1], v[178:179] op_sel_hi:[1,1,0]
	s_nop 0
	v_mul_f32_e32 v7, 0x4b800000, v31
	v_cmp_gt_f32_e64 s[0:1], s88, v31
	v_mul_f32_e32 v9, 0x4b800000, v30
	v_cmp_gt_f32_e64 s[36:37], s88, v30
	v_cndmask_b32_e64 v7, v31, v7, s[0:1]
	v_rsq_f32_e32 v7, v7
	v_cndmask_b32_e64 v9, v30, v9, s[36:37]
	v_rsq_f32_e32 v9, v9
	v_mul_f32_e32 v11, 0x45800000, v7
	v_cndmask_b32_e64 v7, v7, v11, s[0:1]
	v_readlane_b32 s0, v254, 52
	global_store_dword v[38:39], v7, off
	v_mul_f32_e32 v7, 0x45800000, v9
	v_readlane_b32 s1, v254, 53
	v_cndmask_b32_e64 v7, v9, v7, s[36:37]
	s_nop 0
	v_lshl_add_u64 v[30:31], s[0:1], 0, v[36:37]
	global_store_dword v[30:31], v7, off
	s_branch .LBB0_520
